# EpiResid front (3 FFN-out instances): the four serialized coef*mod vector loads get own temp quads, all 12 vector loads issued together with one wait (was 4 round trips)
# speedup vs baseline: 1.0064x; 1.0029x over previous
;     __device__ __forceinline__ void operator()(const f32x4 (&acc)[2][2][4][2], const Unit& u, int wr, int wc, int fr, int fq) const {
;         const int b = (u.pm * BM) >> 11; const float cf_ = coef;
;         const int colb = u.pn * BM + wc * 32 + fq * 4;
;         f32x4 gvv[2][2], gsv[2][2], rgv[2][2];
; #pragma unroll
;         for (int bj = 0; bj < 2; ++bj)
; #pragma unroll
;             for (int n = 0; n < 2; ++n) { const f32x4 t_ = *(const f32x4*)(modp + (size_t)b * 9216 + colb + bj * HALF + n * 16); gvv[bj][n] = (f32x4){t_[0] * cf_, t_[1] * cf_, t_[2] * cf_, t_[3] * cf_};
;                 if (HAS_AN) gsv[bj][n] = *(const f32x4*)(gs + (size_t)b * 1024 + colb + bj * HALF + n * 16);
;                 if (!FROM_F32) rgv[bj][n] = *(const f32x4*)(rgs + (size_t)b * 1024 + colb + bj * HALF + n * 16); }
;         const size_t rowoff = (size_t)(u.pm * BM + wr * 64 + fr) * DM + colb;
;         const float* __restrict__ basep = xp + rowoff;
;         float* __restrict__ outp = X + rowoff;
;         bf16_t* anp = An + rowoff;
;         float* ssqp = ssq + u.pm * BM + wr * 64 + fr;
; #pragma unroll
;         for (int ai = 0; ai < 2; ++ai) {
;             f32x4 bsf[FROM_F32 ? 2 : 1][2][2]; u32x2 bsh[FROM_F32 ? 1 : 4][2][2];
;             if (!FROM_F32) {
; #pragma unroll
;                 for (int m = 0; m < 4; ++m)
; #pragma unroll
;                     for (int bj = 0; bj < 2; ++bj)
; #pragma unroll
;                         for (int n = 0; n < 2; ++n) bsh[m][bj][n] = *(const u32x2*)(anp + (size_t)(ai * HALF + m * 16) * DM + bj * HALF + n * 16);
;             }
; #pragma unroll
;             for (int mp = 0; mp < 2; ++mp) {
;                 if (FROM_F32) {
; #pragma unroll
;                     for (int mm = 0; mm < 2; ++mm)
; #pragma unroll
;                         for (int bj = 0; bj < 2; ++bj)
; #pragma unroll
;                             for (int n = 0; n < 2; ++n) bsf[mm][bj][n] = *(const f32x4*)(basep + (size_t)(ai * HALF + (2 * mp + mm) * 16) * DM + bj * HALF + n * 16);
;                 }
; #pragma unroll
;                 for (int mm = 0; mm < 2; ++mm) {
;                     const int m = 2 * mp + mm; const size_t ro = (size_t)(ai * HALF + m * 16) * DM; float sq = 0.f;
; #pragma unroll
;                     for (int bj = 0; bj < 2; ++bj)
; #pragma unroll
;                         for (int n = 0; n < 2; ++n) {
.LBB0_363:
	s_ashr_i32 s20, s97, 3
	v_lshl_or_b32 v186, s17, 8, v181
	s_ashr_i32 s21, s20, 31
	s_mul_i32 s28, s20, 0x9000
	s_mul_hi_i32 s17, s20, 0x9000
	s_add_u32 s28, s36, s28
	v_ashrrev_i32_e32 v187, 31, v186
	s_addc_u32 s29, s37, s17
	v_lshlrev_b64 v[60:61], 2, v[186:187]
	s_lshl_b64 s[20:21], s[20:21], 12
	v_lshl_add_u64 v[72:73], s[28:29], 0, v[60:61]
	s_add_u32 s28, s38, s20
	s_addc_u32 s29, s39, s21
	s_add_u32 s20, s34, s20
	s_addc_u32 s21, s35, s21
	v_lshl_add_u64 v[74:75], s[28:29], 0, v[60:61]
	v_lshl_add_u64 v[204:205], s[20:21], 0, v[60:61]
	global_load_dwordx4 v[208:211], v[72:73], off
	s_lshl_b32 s20, s97, 8
	s_mov_b32 s17, 0x8000
	s_ashr_i32 s21, s20, 31
	global_load_dwordx4 v[76:79], v[74:75], off
	global_load_dwordx4 v[92:95], v[204:205], off
	global_load_dwordx4 v[212:215], v[72:73], off offset:64
	global_load_dwordx4 v[68:71], v[74:75], off offset:64
	global_load_dwordx4 v[88:91], v[204:205], off offset:64
	global_load_dwordx4 v[216:219], v[72:73], off offset:512
	global_load_dwordx4 v[64:67], v[74:75], off offset:512
	global_load_dwordx4 v[80:83], v[204:205], off offset:512
	global_load_dwordx4 v[220:223], v[72:73], off offset:576
	global_load_dwordx4 v[60:63], v[74:75], off offset:576
	s_nop 0
	global_load_dwordx4 v[72:75], v[204:205], off offset:576
	s_waitcnt vmcnt(0)
	v_pk_mul_f32 v[200:201], v[210:211], 0.5 op_sel_hi:[1,0]
	v_pk_mul_f32 v[202:203], v[208:209], 0.5 op_sel_hi:[1,0]
	v_pk_mul_f32 v[196:197], v[214:215], 0.5 op_sel_hi:[1,0]
	v_pk_mul_f32 v[198:199], v[212:213], 0.5 op_sel_hi:[1,0]
	v_pk_mul_f32 v[192:193], v[218:219], 0.5 op_sel_hi:[1,0]
	v_pk_mul_f32 v[194:195], v[216:217], 0.5 op_sel_hi:[1,0]
	v_pk_mul_f32 v[188:189], v[222:223], 0.5 op_sel_hi:[1,0]
	v_pk_mul_f32 v[190:191], v[220:221], 0.5 op_sel_hi:[1,0]
	v_add_u32_e32 v204, s20, v169
	v_ashrrev_i32_e32 v205, 31, v204
	v_lshlrev_b64 v[204:205], 11, v[204:205]
	v_lshl_add_u64 v[204:205], s[42:43], 0, v[204:205]
	v_lshl_add_u64 v[204:205], v[186:187], 1, v[204:205]
	global_load_dwordx2 v[240:241], v[204:205], off
	global_load_dwordx2 v[234:235], v[204:205], off offset:32
	global_load_dwordx2 v[232:233], v[204:205], off offset:256
	global_load_dwordx2 v[230:231], v[204:205], off offset:288
	v_add_co_u32_e32 v206, vcc, s17, v204
	s_mov_b32 s17, 0x10000
	s_nop 0
	v_addc_co_u32_e32 v207, vcc, 0, v205, vcc
	global_load_dwordx2 v[228:229], v[206:207], off
	global_load_dwordx2 v[226:227], v[206:207], off offset:32
	global_load_dwordx2 v[224:225], v[206:207], off offset:256
	global_load_dwordx2 v[222:223], v[206:207], off offset:288
	v_add_co_u32_e32 v206, vcc, s17, v204
	s_mov_b32 s17, 0x18000
	s_nop 0
	v_addc_co_u32_e32 v207, vcc, 0, v205, vcc
	global_load_dwordx2 v[220:221], v[206:207], off
	global_load_dwordx2 v[218:219], v[206:207], off offset:32
	global_load_dwordx2 v[216:217], v[206:207], off offset:256
	global_load_dwordx2 v[212:213], v[206:207], off offset:288
	v_add_co_u32_e32 v206, vcc, s17, v204
	v_lshl_add_u64 v[186:187], s[20:21], 2, v[166:167]
	s_nop 0
	v_addc_co_u32_e32 v207, vcc, 0, v205, vcc
	global_load_dwordx2 v[214:215], v[206:207], off
	global_load_dwordx2 v[210:211], v[206:207], off offset:32
	global_load_dwordx2 v[208:209], v[206:207], off offset:256
	s_nop 0
	global_load_dwordx2 v[206:207], v[206:207], off offset:288
	s_waitcnt vmcnt(15)
	v_lshlrev_b32_e32 v242, 16, v240
	v_and_b32_e32 v243, 0xffff0000, v240
	v_lshlrev_b32_e32 v240, 16, v241
	v_and_b32_e32 v241, 0xffff0000, v241
	v_pk_mul_f32 v[242:243], v[92:93], v[242:243]
	v_pk_mul_f32 v[240:241], v[94:95], v[240:241]
	v_pk_fma_f32 v[156:157], v[156:157], v[202:203], v[242:243]
	v_pk_fma_f32 v[158:159], v[158:159], v[200:201], v[240:241]
	v_mul_f32_e32 v240, v157, v157
	v_fmac_f32_e32 v240, v156, v156
	v_fmac_f32_e32 v240, v158, v158
	v_fmac_f32_e32 v240, v159, v159
	v_pk_mul_f32 v[158:159], v[78:79], v[158:159]
	v_pk_mul_f32 v[156:157], v[76:77], v[156:157]
	s_nop 0
	v_cvt_pk_bf16_f32 v156, v156, v157
	v_cvt_pk_bf16_f32 v157, v158, v159
	global_store_dwordx2 v[204:205], v[156:157], off
	s_waitcnt vmcnt(15)
	v_lshlrev_b32_e32 v156, 16, v234
	v_and_b32_e32 v157, 0xffff0000, v234
	v_pk_mul_f32 v[156:157], v[88:89], v[156:157]
	v_lshlrev_b32_e32 v158, 16, v235
	v_and_b32_e32 v159, 0xffff0000, v235
	v_pk_fma_f32 v[152:153], v[152:153], v[198:199], v[156:157]
	v_pk_mul_f32 v[158:159], v[90:91], v[158:159]
	v_mul_f32_e32 v156, v153, v153
	v_pk_fma_f32 v[154:155], v[154:155], v[196:197], v[158:159]
	v_fmac_f32_e32 v156, v152, v152
	v_fmac_f32_e32 v156, v154, v154
	v_fmac_f32_e32 v156, v155, v155
	v_pk_mul_f32 v[154:155], v[70:71], v[154:155]
	v_pk_mul_f32 v[152:153], v[68:69], v[152:153]
	v_add_f32_e32 v156, v240, v156
	v_cvt_pk_bf16_f32 v152, v152, v153
	v_cvt_pk_bf16_f32 v153, v154, v155
	global_store_dwordx2 v[204:205], v[152:153], off offset:32
	s_waitcnt vmcnt(15)
	v_lshlrev_b32_e32 v152, 16, v232
	v_and_b32_e32 v153, 0xffff0000, v232
	v_pk_mul_f32 v[152:153], v[80:81], v[152:153]
	v_lshlrev_b32_e32 v154, 16, v233
	v_and_b32_e32 v155, 0xffff0000, v233
	v_pk_fma_f32 v[148:149], v[148:149], v[194:195], v[152:153]
	v_pk_mul_f32 v[154:155], v[82:83], v[154:155]
	v_mul_f32_e32 v152, v149, v149
	v_pk_fma_f32 v[150:151], v[150:151], v[192:193], v[154:155]
	v_fmac_f32_e32 v152, v148, v148
	v_fmac_f32_e32 v152, v150, v150
	v_fmac_f32_e32 v152, v151, v151
	v_pk_mul_f32 v[150:151], v[66:67], v[150:151]
	v_pk_mul_f32 v[148:149], v[64:65], v[148:149]
	v_add_f32_e32 v152, v156, v152
	v_cvt_pk_bf16_f32 v148, v148, v149
	v_cvt_pk_bf16_f32 v149, v150, v151
	global_store_dwordx2 v[204:205], v[148:149], off offset:256
	s_waitcnt vmcnt(15)
	v_lshlrev_b32_e32 v148, 16, v230
	v_and_b32_e32 v149, 0xffff0000, v230
	v_pk_mul_f32 v[148:149], v[72:73], v[148:149]
	v_lshlrev_b32_e32 v150, 16, v231
	v_and_b32_e32 v151, 0xffff0000, v231
	v_pk_fma_f32 v[144:145], v[144:145], v[190:191], v[148:149]
	v_pk_mul_f32 v[150:151], v[74:75], v[150:151]
	v_mul_f32_e32 v148, v145, v145
	v_pk_fma_f32 v[146:147], v[146:147], v[188:189], v[150:151]
	v_fmac_f32_e32 v148, v144, v144
	v_fmac_f32_e32 v148, v146, v146
	v_fmac_f32_e32 v148, v147, v147
	v_pk_mul_f32 v[146:147], v[62:63], v[146:147]
	v_pk_mul_f32 v[144:145], v[60:61], v[144:145]
	v_add_f32_e32 v148, v152, v148
	v_cvt_pk_bf16_f32 v144, v144, v145
	v_cvt_pk_bf16_f32 v145, v146, v147
	global_store_dwordx2 v[204:205], v[144:145], off offset:288
	v_mov_b32_e32 v144, v148
	s_nop 1
	v_permlane16_swap_b32_e32 v148, v144
	v_add_f32_e32 v144, v148, v144
	v_mov_b32_e32 v145, v144
	s_nop 1
	v_permlane32_swap_b32_e32 v144, v145
	s_and_saveexec_b64 s[58:59], s[4:5]
	s_cbranch_execz .LBB0_365
	v_add_f32_e32 v144, v144, v145
	global_atomic_add_f32 v[186:187], v144, off

;     __device__ __forceinline__ void operator()(const f32x4 (&acc)[2][2][4][2], const Unit& u, int wr, int wc, int fr, int fq) const {
;         const int b = (u.pm * BM) >> 11; const float cf_ = coef;
;         const int colb = u.pn * BM + wc * 32 + fq * 4;
;         f32x4 gvv[2][2], gsv[2][2], rgv[2][2];
; #pragma unroll
;         for (int bj = 0; bj < 2; ++bj)
; #pragma unroll
;             for (int n = 0; n < 2; ++n) { const f32x4 t_ = *(const f32x4*)(modp + (size_t)b * 9216 + colb + bj * HALF + n * 16); gvv[bj][n] = (f32x4){t_[0] * cf_, t_[1] * cf_, t_[2] * cf_, t_[3] * cf_};
;                 if (HAS_AN) gsv[bj][n] = *(const f32x4*)(gs + (size_t)b * 1024 + colb + bj * HALF + n * 16);
;                 if (!FROM_F32) rgv[bj][n] = *(const f32x4*)(rgs + (size_t)b * 1024 + colb + bj * HALF + n * 16); }
;         const size_t rowoff = (size_t)(u.pm * BM + wr * 64 + fr) * DM + colb;
;         const float* __restrict__ basep = xp + rowoff;
;         float* __restrict__ outp = X + rowoff;
;         bf16_t* anp = An + rowoff;
;         float* ssqp = ssq + u.pm * BM + wr * 64 + fr;
; #pragma unroll
;         for (int ai = 0; ai < 2; ++ai) {
;             f32x4 bsf[FROM_F32 ? 2 : 1][2][2]; u32x2 bsh[FROM_F32 ? 1 : 4][2][2];
;             if (!FROM_F32) {
; #pragma unroll
;                 for (int m = 0; m < 4; ++m)
; #pragma unroll
;                     for (int bj = 0; bj < 2; ++bj)
; #pragma unroll
;                         for (int n = 0; n < 2; ++n) bsh[m][bj][n] = *(const u32x2*)(anp + (size_t)(ai * HALF + m * 16) * DM + bj * HALF + n * 16);
;             }
; #pragma unroll
;             for (int mp = 0; mp < 2; ++mp) {
;                 if (FROM_F32) {
; #pragma unroll
;                     for (int mm = 0; mm < 2; ++mm)
; #pragma unroll
;                         for (int bj = 0; bj < 2; ++bj)
; #pragma unroll
;                             for (int n = 0; n < 2; ++n) bsf[mm][bj][n] = *(const f32x4*)(basep + (size_t)(ai * HALF + (2 * mp + mm) * 16) * DM + bj * HALF + n * 16);
;                 }
; #pragma unroll
;                 for (int mm = 0; mm < 2; ++mm) {
;                     const int m = 2 * mp + mm; const size_t ro = (size_t)(ai * HALF + m * 16) * DM; float sq = 0.f;
; #pragma unroll
;                     for (int bj = 0; bj < 2; ++bj)
; #pragma unroll
;                         for (int n = 0; n < 2; ++n) {
.LBB0_1092:
	s_ashr_i32 s46, s81, 3
	v_lshl_or_b32 v170, s82, 8, v247
	s_ashr_i32 s47, s46, 31
	s_mul_i32 s58, s46, 0x9000
	s_mul_hi_i32 s59, s46, 0x9000
	s_add_u32 s58, s22, s58
	v_ashrrev_i32_e32 v171, 31, v170
	s_addc_u32 s59, s23, s59
	v_lshlrev_b64 v[60:61], 2, v[170:171]
	s_lshl_b64 s[46:47], s[46:47], 12
	v_lshl_add_u64 v[72:73], s[58:59], 0, v[60:61]
	s_add_u32 s58, s34, s46
	s_addc_u32 s59, s35, s47
	s_add_u32 s46, s36, s46
	s_addc_u32 s47, s37, s47
	v_lshl_add_u64 v[74:75], s[58:59], 0, v[60:61]
	v_lshl_add_u64 v[206:207], s[46:47], 0, v[60:61]
	global_load_dwordx4 v[208:211], v[72:73], off
	s_lshl_b32 s46, s81, 8
	s_ashr_i32 s47, s46, 31
	global_load_dwordx4 v[76:79], v[74:75], off
	global_load_dwordx4 v[92:95], v[206:207], off
	global_load_dwordx4 v[212:215], v[72:73], off offset:64
	global_load_dwordx4 v[68:71], v[74:75], off offset:64
	global_load_dwordx4 v[88:91], v[206:207], off offset:64
	global_load_dwordx4 v[216:219], v[72:73], off offset:512
	global_load_dwordx4 v[64:67], v[74:75], off offset:512
	global_load_dwordx4 v[80:83], v[206:207], off offset:512
	global_load_dwordx4 v[220:223], v[72:73], off offset:576
	global_load_dwordx4 v[60:63], v[74:75], off offset:576
	s_nop 0
	global_load_dwordx4 v[72:75], v[206:207], off offset:576
	s_waitcnt vmcnt(0)
	v_pk_mul_f32 v[202:203], v[210:211], 0.5 op_sel_hi:[1,0]
	v_pk_mul_f32 v[204:205], v[208:209], 0.5 op_sel_hi:[1,0]
	v_pk_mul_f32 v[198:199], v[214:215], 0.5 op_sel_hi:[1,0]
	v_pk_mul_f32 v[200:201], v[212:213], 0.5 op_sel_hi:[1,0]
	v_pk_mul_f32 v[194:195], v[218:219], 0.5 op_sel_hi:[1,0]
	v_pk_mul_f32 v[196:197], v[216:217], 0.5 op_sel_hi:[1,0]
	v_pk_mul_f32 v[172:173], v[222:223], 0.5 op_sel_hi:[1,0]
	v_pk_mul_f32 v[174:175], v[220:221], 0.5 op_sel_hi:[1,0]
	v_add_u32_e32 v206, s46, v185
	v_ashrrev_i32_e32 v207, 31, v206
	v_lshlrev_b64 v[206:207], 11, v[206:207]
	v_lshl_add_u64 v[206:207], s[42:43], 0, v[206:207]
	v_lshl_add_u64 v[206:207], v[170:171], 1, v[206:207]
	global_load_dwordx2 v[240:241], v[206:207], off
	global_load_dwordx2 v[236:237], v[206:207], off offset:32
	global_load_dwordx2 v[234:235], v[206:207], off offset:256
	global_load_dwordx2 v[232:233], v[206:207], off offset:288
	v_lshl_add_u64 v[170:171], s[46:47], 2, v[164:165]
	s_mov_b32 s46, 0x8000
	v_add_co_u32_e32 v208, vcc, s46, v206
	s_mov_b32 s46, 0x10000
	s_nop 0
	v_addc_co_u32_e32 v209, vcc, 0, v207, vcc
	global_load_dwordx2 v[230:231], v[208:209], off
	global_load_dwordx2 v[228:229], v[208:209], off offset:32
	global_load_dwordx2 v[226:227], v[208:209], off offset:256
	global_load_dwordx2 v[224:225], v[208:209], off offset:288
	v_add_co_u32_e32 v208, vcc, s46, v206
	s_mov_b32 s46, 0x18000
	s_nop 0
	v_addc_co_u32_e32 v209, vcc, 0, v207, vcc
	global_load_dwordx2 v[222:223], v[208:209], off
	global_load_dwordx2 v[220:221], v[208:209], off offset:32
	global_load_dwordx2 v[218:219], v[208:209], off offset:256
	global_load_dwordx2 v[214:215], v[208:209], off offset:288
	v_add_co_u32_e32 v208, vcc, s46, v206
	s_waitcnt vmcnt(11)
	v_lshlrev_b32_e32 v242, 16, v240
	v_addc_co_u32_e32 v209, vcc, 0, v207, vcc
	global_load_dwordx2 v[216:217], v[208:209], off
	global_load_dwordx2 v[212:213], v[208:209], off offset:32
	global_load_dwordx2 v[210:211], v[208:209], off offset:256
	s_nop 0
	global_load_dwordx2 v[208:209], v[208:209], off offset:288
	v_and_b32_e32 v243, 0xffff0000, v240
	v_lshlrev_b32_e32 v240, 16, v241
	v_and_b32_e32 v241, 0xffff0000, v241
	v_pk_mul_f32 v[242:243], v[92:93], v[242:243]
	v_pk_mul_f32 v[240:241], v[94:95], v[240:241]
	v_pk_fma_f32 v[156:157], v[156:157], v[204:205], v[242:243]
	v_pk_fma_f32 v[158:159], v[158:159], v[202:203], v[240:241]
	v_mul_f32_e32 v240, v157, v157
	v_fmac_f32_e32 v240, v156, v156
	v_fmac_f32_e32 v240, v158, v158
	v_fmac_f32_e32 v240, v159, v159
	v_pk_mul_f32 v[158:159], v[78:79], v[158:159]
	v_pk_mul_f32 v[156:157], v[76:77], v[156:157]
	s_nop 0
	v_cvt_pk_bf16_f32 v156, v156, v157
	v_cvt_pk_bf16_f32 v157, v158, v159
	global_store_dwordx2 v[206:207], v[156:157], off
	s_waitcnt vmcnt(15)
	v_lshlrev_b32_e32 v156, 16, v236
	v_and_b32_e32 v157, 0xffff0000, v236
	v_pk_mul_f32 v[156:157], v[88:89], v[156:157]
	v_lshlrev_b32_e32 v158, 16, v237
	v_and_b32_e32 v159, 0xffff0000, v237
	v_pk_fma_f32 v[152:153], v[152:153], v[200:201], v[156:157]
	v_pk_mul_f32 v[158:159], v[90:91], v[158:159]
	v_mul_f32_e32 v156, v153, v153
	v_pk_fma_f32 v[154:155], v[154:155], v[198:199], v[158:159]
	v_fmac_f32_e32 v156, v152, v152
	v_fmac_f32_e32 v156, v154, v154
	v_fmac_f32_e32 v156, v155, v155
	v_pk_mul_f32 v[154:155], v[70:71], v[154:155]
	v_pk_mul_f32 v[152:153], v[68:69], v[152:153]
	v_add_f32_e32 v156, v240, v156
	v_cvt_pk_bf16_f32 v152, v152, v153
	v_cvt_pk_bf16_f32 v153, v154, v155
	global_store_dwordx2 v[206:207], v[152:153], off offset:32
	s_waitcnt vmcnt(15)
	v_lshlrev_b32_e32 v152, 16, v234
	v_and_b32_e32 v153, 0xffff0000, v234
	v_pk_mul_f32 v[152:153], v[80:81], v[152:153]
	v_lshlrev_b32_e32 v154, 16, v235
	v_and_b32_e32 v155, 0xffff0000, v235
	v_pk_fma_f32 v[148:149], v[148:149], v[196:197], v[152:153]
	v_pk_mul_f32 v[154:155], v[82:83], v[154:155]
	v_mul_f32_e32 v152, v149, v149
	v_pk_fma_f32 v[150:151], v[150:151], v[194:195], v[154:155]
	v_fmac_f32_e32 v152, v148, v148
	v_fmac_f32_e32 v152, v150, v150
	v_fmac_f32_e32 v152, v151, v151
	v_pk_mul_f32 v[150:151], v[66:67], v[150:151]
	v_pk_mul_f32 v[148:149], v[64:65], v[148:149]
	v_add_f32_e32 v152, v156, v152
	v_cvt_pk_bf16_f32 v148, v148, v149
	v_cvt_pk_bf16_f32 v149, v150, v151
	global_store_dwordx2 v[206:207], v[148:149], off offset:256
	s_waitcnt vmcnt(15)
	v_lshlrev_b32_e32 v148, 16, v232
	v_and_b32_e32 v149, 0xffff0000, v232
	v_pk_mul_f32 v[148:149], v[72:73], v[148:149]
	v_lshlrev_b32_e32 v150, 16, v233
	v_and_b32_e32 v151, 0xffff0000, v233
	v_pk_fma_f32 v[144:145], v[144:145], v[174:175], v[148:149]
	v_pk_mul_f32 v[150:151], v[74:75], v[150:151]
	v_mul_f32_e32 v148, v145, v145
	v_pk_fma_f32 v[146:147], v[146:147], v[172:173], v[150:151]
	v_fmac_f32_e32 v148, v144, v144
	v_fmac_f32_e32 v148, v146, v146
	v_fmac_f32_e32 v148, v147, v147
	v_pk_mul_f32 v[146:147], v[62:63], v[146:147]
	v_pk_mul_f32 v[144:145], v[60:61], v[144:145]
	v_add_f32_e32 v148, v152, v148
	v_cvt_pk_bf16_f32 v144, v144, v145
	v_cvt_pk_bf16_f32 v145, v146, v147
	global_store_dwordx2 v[206:207], v[144:145], off offset:288
	v_mov_b32_e32 v144, v148
	s_nop 1
	v_permlane16_swap_b32_e32 v148, v144
	v_add_f32_e32 v144, v148, v144
	v_mov_b32_e32 v145, v144
	s_nop 1
	v_permlane32_swap_b32_e32 v144, v145
	s_and_saveexec_b64 s[58:59], s[12:13]
	s_cbranch_execz .LBB0_1094
	v_add_f32_e32 v144, v144, v145
	global_atomic_add_f32 v[170:171], v144, off
